# plus SB loop trims (clamp canonicalize removed, cumsum copy removed, QK reads hoisted), SWA gate loads hoisted per head
# speedup vs baseline: 1.0072x; 1.0072x over previous
; __device__ __forceinline__ unsigned cvtpk(float lo, float hi) { f32x2_t v = {lo, hi}; bf16x2_t b = __builtin_convertvector(v, bf16x2_t); return __builtin_bit_cast(unsigned, b); }
; __device__ __forceinline__ float bf_lo(unsigned w) { return __uint_as_float(w << 16); }
; __device__ __forceinline__ float bf_hi(unsigned w) { return __uint_as_float(w & 0xffff0000u); }
; __device__ __forceinline__ float half_sum(float m) { auto rr = __builtin_amdgcn_permlane32_swap(__float_as_uint(m), __float_as_uint(m), false, false); return __uint_as_float(rr[0]) + __uint_as_float(rr[1]); }
; __device__ __forceinline__ float silu_f(float x) { return x * __builtin_amdgcn_rcpf(1.f + __expf(-x)); }
; __device__ __forceinline__ void swa_unit(int b, int kvh, int qb, const bf16* U, const bf16* VTb, bf16* Y, const float* sinks, const float* qgain, const int* pos, unsigned char* lds, int wid, int lane) {
;     ...
;         const float inv = 1.0f / half_sum(l);
;         const bf16* gbr = U + (rowbase + tq) * EU + C_GB + qh * 64;
;         bf16* yr = Y + (rowbase + tq) * D + 512 + qh * 64; u32x2 wprev = {0u, 0u};
; #pragma unroll
;         for (int db = 0; db < 2; ++db)
; #pragma unroll
;             for (int g4 = 0; g4 < 4; ++g4) {
;                 const int e = 32 * db + 8 * g4 + 4 * hi;
;                 const u32x2 gw = *(const u32x2*)(gbr + e);
;                 const float y0 = o[db][4 * g4 + 0] * inv * silu_f(bf_lo(gw.x)), y1 = o[db][4 * g4 + 1] * inv * silu_f(bf_hi(gw.x));
;                 const float y2 = o[db][4 * g4 + 2] * inv * silu_f(bf_lo(gw.y)), y3 = o[db][4 * g4 + 3] * inv * silu_f(bf_hi(gw.y));
;                 u32x2 w; w.x = cvtpk(y0, y1); w.y = cvtpk(y2, y3);
;                 if ((g4 & 1) == 0) wprev = w; else store_pair16(yr + 32 * db + 16 * (g4 >> 1) + 8 * hi, wprev, w);
;             }
.LBB0_456:
	s_lshl_b32 s0, s14, 6
	s_lshl_b32 s2, s0, 1
	v_lshl_add_u64 v[4:5], v[114:115], 0, s[2:3]
	s_waitcnt vmcnt(0)
	v_mov_b32_e32 v0, v3
	s_nop 1
	v_permlane32_swap_b32_e32 v3, v0
	v_add_f32_e32 v0, v3, v0
	v_div_scale_f32 v10, s[0:1], v0, v0, 1.0
	v_rcp_f32_e32 v11, v10
	v_div_scale_f32 v12, vcc, 1.0, v0, 1.0
	v_lshl_add_u64 v[2:3], v[112:113], 0, s[2:3]
	v_fma_f32 v13, -v10, v11, 1.0
	v_fmac_f32_e32 v11, v13, v11
	v_mul_f32_e32 v13, v12, v11
	v_fma_f32 v14, -v10, v13, v12
	v_fmac_f32_e32 v13, v14, v11
	v_fma_f32 v10, -v10, v13, v12
	v_div_fmas_f32 v10, v10, v11, v13
	v_div_fixup_f32 v0, v10, v0, 1.0
	v_pk_mul_f32 v[10:11], v[32:33], v[0:1] op_sel_hi:[1,0]
	v_pk_mul_f32 v[12:13], v[34:35], v[0:1] op_sel_hi:[1,0]
	v_pk_mul_f32 v[14:15], v[38:39], v[0:1] op_sel_hi:[1,0]
	v_pk_mul_f32 v[32:33], v[36:37], v[0:1] op_sel_hi:[1,0]
	s_add_i32 s24, s24, 1
	s_cmp_eq_u32 s24, 4
	v_mov_b64_e32 v[6:7], v[144:145]
	v_mov_b64_e32 v[8:9], v[146:147]
	v_lshlrev_b32_e32 v34, 16, v6
	v_and_b32_e32 v35, 0xffff0000, v6
	v_lshlrev_b32_e32 v6, 16, v7
	v_and_b32_e32 v7, 0xffff0000, v7
	v_lshlrev_b32_e32 v36, 16, v9
	v_and_b32_e32 v37, 0xffff0000, v9
	v_lshlrev_b32_e32 v38, 16, v8
	v_and_b32_e32 v39, 0xffff0000, v8
	v_mul_f32_e32 v8, 0xbfb8aa3b, v34
	v_mul_f32_e32 v9, 0xbfb8aa3b, v35
	v_mul_f32_e32 v48, 0xbfb8aa3b, v6
	v_mul_f32_e32 v49, 0xbfb8aa3b, v7
	v_mul_f32_e32 v50, 0xbfb8aa3b, v36
	v_mul_f32_e32 v51, 0xbfb8aa3b, v37
	v_mul_f32_e32 v52, 0xbfb8aa3b, v38
	v_mul_f32_e32 v53, 0xbfb8aa3b, v39
	v_exp_f32_e32 v8, v8
	v_exp_f32_e32 v9, v9
	v_exp_f32_e32 v48, v48
	v_exp_f32_e32 v49, v49
	v_exp_f32_e32 v50, v50
	v_exp_f32_e32 v51, v51
	v_exp_f32_e32 v52, v52
	v_exp_f32_e32 v53, v53
	v_add_f32_e32 v8, 1.0, v8
	v_add_f32_e32 v9, 1.0, v9
	v_add_f32_e32 v48, 1.0, v48
	v_add_f32_e32 v49, 1.0, v49
	v_add_f32_e32 v50, 1.0, v50
	v_add_f32_e32 v51, 1.0, v51
	v_add_f32_e32 v52, 1.0, v52
	v_add_f32_e32 v53, 1.0, v53
	v_rcp_f32_e32 v8, v8
	v_rcp_f32_e32 v9, v9
	v_rcp_f32_e32 v48, v48
	v_rcp_f32_e32 v49, v49
	v_rcp_f32_e32 v50, v50
	v_rcp_f32_e32 v51, v51
	v_rcp_f32_e32 v52, v52
	v_rcp_f32_e32 v53, v53
	v_pk_mul_f32 v[8:9], v[8:9], v[34:35]
	v_pk_mul_f32 v[6:7], v[48:49], v[6:7]
	v_pk_mul_f32 v[34:35], v[50:51], v[36:37]
	v_pk_mul_f32 v[36:37], v[52:53], v[38:39]
	v_pk_mul_f32 v[8:9], v[10:11], v[8:9]
	v_pk_mul_f32 v[10:11], v[12:13], v[6:7]
	v_pk_mul_f32 v[12:13], v[14:15], v[34:35]
	v_pk_mul_f32 v[14:15], v[32:33], v[36:37]
	v_cvt_pk_bf16_f32 v6, v8, v9
	v_cvt_pk_bf16_f32 v7, v10, v11
	v_cvt_pk_bf16_f32 v9, v12, v13
	v_cvt_pk_bf16_f32 v8, v14, v15
	s_nop 1
	v_permlane32_swap_b32_e32 v6, v8
	v_permlane32_swap_b32_e32 v7, v9
	global_store_dwordx4 v[2:3], v[6:9], off offset:1024
	s_nop 1
	v_mov_b64_e32 v[6:7], v[148:149]
	v_mov_b64_e32 v[8:9], v[150:151]
	v_pk_mul_f32 v[10:11], v[40:41], v[0:1] op_sel_hi:[1,0]
	v_pk_mul_f32 v[12:13], v[42:43], v[0:1] op_sel_hi:[1,0]
	v_pk_mul_f32 v[32:33], v[44:45], v[0:1] op_sel_hi:[1,0]
	v_pk_mul_f32 v[14:15], v[46:47], v[0:1] op_sel_hi:[1,0]
	v_lshlrev_b32_e32 v34, 16, v6
	v_and_b32_e32 v35, 0xffff0000, v6
	v_lshlrev_b32_e32 v6, 16, v7
	v_and_b32_e32 v7, 0xffff0000, v7
	v_lshlrev_b32_e32 v36, 16, v9
	v_and_b32_e32 v37, 0xffff0000, v9
	v_lshlrev_b32_e32 v38, 16, v8
	v_and_b32_e32 v39, 0xffff0000, v8
	v_mul_f32_e32 v8, 0xbfb8aa3b, v34
	v_mul_f32_e32 v9, 0xbfb8aa3b, v35
	v_mul_f32_e32 v40, 0xbfb8aa3b, v6
	v_mul_f32_e32 v41, 0xbfb8aa3b, v7
	v_mul_f32_e32 v42, 0xbfb8aa3b, v36
	v_mul_f32_e32 v43, 0xbfb8aa3b, v37
	v_mul_f32_e32 v44, 0xbfb8aa3b, v38
	v_mul_f32_e32 v45, 0xbfb8aa3b, v39
	v_exp_f32_e32 v8, v8
	v_exp_f32_e32 v9, v9
	v_exp_f32_e32 v40, v40
	v_exp_f32_e32 v41, v41
	v_exp_f32_e32 v42, v42
	v_exp_f32_e32 v43, v43
	v_exp_f32_e32 v44, v44
	v_exp_f32_e32 v45, v45
	v_add_f32_e32 v8, 1.0, v8
	v_add_f32_e32 v9, 1.0, v9
	v_add_f32_e32 v40, 1.0, v40
	v_add_f32_e32 v41, 1.0, v41
	v_add_f32_e32 v42, 1.0, v42
	v_add_f32_e32 v43, 1.0, v43
	v_add_f32_e32 v44, 1.0, v44
	v_add_f32_e32 v45, 1.0, v45
	v_rcp_f32_e32 v8, v8
	v_rcp_f32_e32 v9, v9
	v_rcp_f32_e32 v40, v40
	v_rcp_f32_e32 v41, v41
	v_rcp_f32_e32 v42, v42
	v_rcp_f32_e32 v43, v43
	v_rcp_f32_e32 v44, v44
	v_rcp_f32_e32 v45, v45
	v_pk_mul_f32 v[8:9], v[8:9], v[34:35]
	v_pk_mul_f32 v[6:7], v[40:41], v[6:7]
	v_pk_mul_f32 v[34:35], v[42:43], v[36:37]
	v_pk_mul_f32 v[36:37], v[44:45], v[38:39]
	v_pk_mul_f32 v[8:9], v[10:11], v[8:9]
	v_pk_mul_f32 v[10:11], v[12:13], v[6:7]
	v_pk_mul_f32 v[12:13], v[14:15], v[34:35]
	v_pk_mul_f32 v[14:15], v[32:33], v[36:37]
	v_cvt_pk_bf16_f32 v6, v8, v9
	v_cvt_pk_bf16_f32 v7, v10, v11
	v_cvt_pk_bf16_f32 v9, v12, v13
	v_cvt_pk_bf16_f32 v8, v14, v15
	s_nop 1
	v_permlane32_swap_b32_e32 v6, v8
	v_permlane32_swap_b32_e32 v7, v9
	global_store_dwordx4 v[2:3], v[6:9], off offset:1056
	s_nop 1
	v_mov_b64_e32 v[6:7], v[152:153]
	v_mov_b64_e32 v[8:9], v[154:155]
	v_pk_mul_f32 v[10:11], v[16:17], v[0:1] op_sel_hi:[1,0]
	v_pk_mul_f32 v[12:13], v[18:19], v[0:1] op_sel_hi:[1,0]
	v_pk_mul_f32 v[14:15], v[22:23], v[0:1] op_sel_hi:[1,0]
	v_pk_mul_f32 v[16:17], v[20:21], v[0:1] op_sel_hi:[1,0]
	v_lshlrev_b32_e32 v18, 16, v6
	v_and_b32_e32 v19, 0xffff0000, v6
	v_lshlrev_b32_e32 v6, 16, v7
	v_and_b32_e32 v7, 0xffff0000, v7
	v_lshlrev_b32_e32 v20, 16, v9
	v_and_b32_e32 v21, 0xffff0000, v9
	v_lshlrev_b32_e32 v22, 16, v8
	v_and_b32_e32 v23, 0xffff0000, v8
	v_mul_f32_e32 v8, 0xbfb8aa3b, v18
	v_mul_f32_e32 v9, 0xbfb8aa3b, v19
	v_mul_f32_e32 v32, 0xbfb8aa3b, v6
	v_mul_f32_e32 v33, 0xbfb8aa3b, v7
	v_mul_f32_e32 v34, 0xbfb8aa3b, v20
	v_mul_f32_e32 v35, 0xbfb8aa3b, v21
	v_mul_f32_e32 v36, 0xbfb8aa3b, v22
	v_mul_f32_e32 v37, 0xbfb8aa3b, v23
	v_exp_f32_e32 v8, v8
	v_exp_f32_e32 v9, v9
; __device__ __forceinline__ unsigned cvtpk(float lo, float hi) { f32x2_t v = {lo, hi}; bf16x2_t b = __builtin_convertvector(v, bf16x2_t); return __builtin_bit_cast(unsigned, b); }
; __device__ __forceinline__ float bf_lo(unsigned w) { return __uint_as_float(w << 16); }
; __device__ __forceinline__ float bf_hi(unsigned w) { return __uint_as_float(w & 0xffff0000u); }
; __device__ __forceinline__ float silu_f(float x) { return x * __builtin_amdgcn_rcpf(1.f + __expf(-x)); }
; __device__ __forceinline__ void swa_unit(int b, int kvh, int qb, const bf16* U, const bf16* VTb, bf16* Y, const float* sinks, const float* qgain, const int* pos, unsigned char* lds, int wid, int lane) {
;     ...
;         { const bf16* qp = U + (rowbase + tq) * EU + C_QB + qh * 64 + hi * 8;
; #pragma unroll
;           for (int ks = 0; ks < 4; ++ks) qf[ks] = *(const bf16x8*)(qp + ks * 16); }
;         q_norm_rope(qf, qgain, pos[rowbase + tq], hi);
;     ...
;                 const int e = 32 * db + 8 * g4 + 4 * hi;
;                 const u32x2 gw = *(const u32x2*)(gbr + e);
;                 const float y0 = o[db][4 * g4 + 0] * inv * silu_f(bf_lo(gw.x)), y1 = o[db][4 * g4 + 1] * inv * silu_f(bf_hi(gw.x));
;                 const float y2 = o[db][4 * g4 + 2] * inv * silu_f(bf_lo(gw.y)), y3 = o[db][4 * g4 + 3] * inv * silu_f(bf_hi(gw.y));
;                 u32x2 w; w.x = cvtpk(y0, y1); w.y = cvtpk(y2, y3);
;                 if ((g4 & 1) == 0) wprev = w; else store_pair16(yr + 32 * db + 16 * (g4 >> 1) + 8 * hi, wprev, w);
;             }
	v_exp_f32_e32 v32, v32
	v_exp_f32_e32 v33, v33
	v_exp_f32_e32 v34, v34
	v_exp_f32_e32 v35, v35
	v_exp_f32_e32 v36, v36
	v_exp_f32_e32 v37, v37
	v_add_f32_e32 v8, 1.0, v8
	v_add_f32_e32 v9, 1.0, v9
	v_add_f32_e32 v32, 1.0, v32
	v_add_f32_e32 v33, 1.0, v33
	v_add_f32_e32 v34, 1.0, v34
	v_add_f32_e32 v35, 1.0, v35
	v_add_f32_e32 v36, 1.0, v36
	v_add_f32_e32 v37, 1.0, v37
	v_rcp_f32_e32 v8, v8
	v_rcp_f32_e32 v9, v9
	v_rcp_f32_e32 v32, v32
	v_rcp_f32_e32 v33, v33
	v_rcp_f32_e32 v34, v34
	v_rcp_f32_e32 v35, v35
	v_rcp_f32_e32 v36, v36
	v_rcp_f32_e32 v37, v37
	v_pk_mul_f32 v[8:9], v[8:9], v[18:19]
	v_pk_mul_f32 v[6:7], v[32:33], v[6:7]
	v_pk_mul_f32 v[18:19], v[34:35], v[20:21]
	v_pk_mul_f32 v[20:21], v[36:37], v[22:23]
	v_pk_mul_f32 v[8:9], v[10:11], v[8:9]
	v_pk_mul_f32 v[10:11], v[12:13], v[6:7]
	v_pk_mul_f32 v[12:13], v[14:15], v[18:19]
	v_pk_mul_f32 v[14:15], v[16:17], v[20:21]
	v_cvt_pk_bf16_f32 v6, v8, v9
	v_cvt_pk_bf16_f32 v7, v10, v11
	v_cvt_pk_bf16_f32 v9, v12, v13
	v_cvt_pk_bf16_f32 v8, v14, v15
	s_nop 1
	v_permlane32_swap_b32_e32 v6, v8
	v_permlane32_swap_b32_e32 v7, v9
	global_store_dwordx4 v[2:3], v[6:9], off offset:1088
	s_nop 1
	v_mov_b64_e32 v[6:7], v[156:157]
	v_mov_b64_e32 v[4:5], v[158:159]
	v_pk_mul_f32 v[8:9], v[24:25], v[0:1] op_sel_hi:[1,0]
	v_pk_mul_f32 v[10:11], v[26:27], v[0:1] op_sel_hi:[1,0]
	v_pk_mul_f32 v[12:13], v[30:31], v[0:1] op_sel_hi:[1,0]
	v_pk_mul_f32 v[14:15], v[28:29], v[0:1] op_sel_hi:[1,0]
	v_lshlrev_b32_e32 v16, 16, v6
	v_and_b32_e32 v17, 0xffff0000, v6
	v_lshlrev_b32_e32 v6, 16, v7
	v_and_b32_e32 v7, 0xffff0000, v7
	v_lshlrev_b32_e32 v18, 16, v5
	v_and_b32_e32 v19, 0xffff0000, v5
	v_lshlrev_b32_e32 v20, 16, v4
	v_and_b32_e32 v21, 0xffff0000, v4
	v_mul_f32_e32 v0, 0xbfb8aa3b, v16
	v_mul_f32_e32 v4, 0xbfb8aa3b, v17
	v_mul_f32_e32 v5, 0xbfb8aa3b, v6
	v_mul_f32_e32 v22, 0xbfb8aa3b, v7
	v_mul_f32_e32 v23, 0xbfb8aa3b, v18
	v_mul_f32_e32 v24, 0xbfb8aa3b, v19
	v_mul_f32_e32 v25, 0xbfb8aa3b, v20
	v_mul_f32_e32 v26, 0xbfb8aa3b, v21
	v_exp_f32_e32 v0, v0
	v_exp_f32_e32 v4, v4
	v_exp_f32_e32 v5, v5
	v_exp_f32_e32 v22, v22
	v_exp_f32_e32 v23, v23
	v_exp_f32_e32 v24, v24
	v_exp_f32_e32 v25, v25
	v_exp_f32_e32 v26, v26
	v_add_f32_e32 v0, 1.0, v0
	v_add_f32_e32 v27, 1.0, v4
	v_add_f32_e32 v28, 1.0, v5
	v_add_f32_e32 v29, 1.0, v22
	v_add_f32_e32 v30, 1.0, v23
	v_add_f32_e32 v31, 1.0, v24
	v_add_f32_e32 v32, 1.0, v25
	v_add_f32_e32 v33, 1.0, v26
	v_rcp_f32_e32 v4, v0
	v_rcp_f32_e32 v5, v27
	v_rcp_f32_e32 v22, v28
	v_rcp_f32_e32 v23, v29
	v_rcp_f32_e32 v24, v30
	v_rcp_f32_e32 v25, v31
	v_rcp_f32_e32 v26, v32
	v_rcp_f32_e32 v27, v33
	v_pk_mul_f32 v[4:5], v[4:5], v[16:17]
	v_pk_mul_f32 v[6:7], v[22:23], v[6:7]
	v_pk_mul_f32 v[16:17], v[24:25], v[18:19]
	v_pk_mul_f32 v[18:19], v[26:27], v[20:21]
	v_pk_mul_f32 v[4:5], v[8:9], v[4:5]
	v_pk_mul_f32 v[6:7], v[10:11], v[6:7]
	v_pk_mul_f32 v[8:9], v[12:13], v[16:17]
	v_pk_mul_f32 v[10:11], v[14:15], v[18:19]
	v_cvt_pk_bf16_f32 v4, v4, v5
	v_cvt_pk_bf16_f32 v5, v6, v7
	v_cvt_pk_bf16_f32 v7, v8, v9
	v_cvt_pk_bf16_f32 v6, v10, v11
	s_nop 1
	v_permlane32_swap_b32_e32 v4, v6
	v_permlane32_swap_b32_e32 v5, v7
	global_store_dwordx4 v[2:3], v[4:7], off offset:1120
	s_cbranch_scc1 .LBB0_451
.LBB0_457:
	s_add_i32 s14, s24, s26
	s_lshl_b32 s2, s14, 7
	v_lshl_add_u64 v[2:3], v[108:109], 0, s[2:3]
	global_load_dwordx4 v[6:9], v[2:3], off offset:3072
	global_load_dwordx4 v[10:13], v[2:3], off offset:3136
	global_load_dwordx4 v[14:17], v[2:3], off offset:3104
	global_load_dwordx4 v[18:21], v[2:3], off offset:3168
	global_load_dword v0, v[110:111], off
	v_lshl_add_u64 v[160:161], v[114:115], 0, s[2:3]
	global_load_dwordx2 v[144:145], v[160:161], off
	global_load_dwordx2 v[146:147], v[160:161], off offset:16
	global_load_dwordx2 v[148:149], v[160:161], off offset:32
	global_load_dwordx2 v[150:151], v[160:161], off offset:48
	global_load_dwordx2 v[152:153], v[160:161], off offset:64
	global_load_dwordx2 v[154:155], v[160:161], off offset:80
	global_load_dwordx2 v[156:157], v[160:161], off offset:96
	global_load_dwordx2 v[158:159], v[160:161], off offset:112
	v_mov_b32_e32 v47, 0
	v_mov_b32_e32 v46, 0
	v_mov_b32_e32 v45, 0
	v_mov_b32_e32 v44, 0
	v_mov_b32_e32 v43, 0
	v_mov_b32_e32 v42, 0
	v_mov_b32_e32 v41, 0
	v_mov_b32_e32 v40, 0
	v_mov_b32_e32 v39, 0
	v_mov_b32_e32 v38, 0
	v_mov_b32_e32 v37, 0
	v_mov_b32_e32 v36, 0
	v_mov_b32_e32 v35, 0
	v_mov_b32_e32 v34, 0
	v_mov_b32_e32 v33, 0
	v_mov_b32_e32 v32, 0
	v_mov_b32_e32 v31, 0
	v_mov_b32_e32 v30, 0
	v_mov_b32_e32 v29, 0
	v_mov_b32_e32 v28, 0
	v_mov_b32_e32 v27, 0
	v_mov_b32_e32 v26, 0
	v_mov_b32_e32 v25, 0
	v_mov_b32_e32 v24, 0
	s_andn2_b64 vcc, exec, s[12:13]
	v_mbcnt_lo_u32_b32 v4, -1, 0
	v_mbcnt_hi_u32_b32 v4, -1, v4
	s_waitcnt vmcnt(12)
	v_and_b32_e32 v63, 0xffff0000, v6
	v_lshlrev_b32_e32 v62, 16, v6
	v_mul_f32_e32 v2, v63, v63
	v_lshlrev_b32_e32 v58, 16, v7
	v_and_b32_e32 v59, 0xffff0000, v7
	v_pk_fma_f32 v[2:3], v[62:63], v[62:63], v[2:3] op_sel_hi:[1,1,0]
	v_mul_f32_e32 v6, v59, v59
	v_pk_fma_f32 v[2:3], v[58:59], v[58:59], v[2:3]
	v_lshlrev_b32_e32 v54, 16, v8
	v_and_b32_e32 v55, 0xffff0000, v8
	v_pk_add_f32 v[2:3], v[6:7], v[2:3] op_sel_hi:[0,1]
	v_mul_f32_e32 v8, v55, v55
	v_pk_fma_f32 v[2:3], v[54:55], v[54:55], v[2:3]
	v_lshlrev_b32_e32 v50, 16, v9
	v_and_b32_e32 v51, 0xffff0000, v9
	v_pk_add_f32 v[2:3], v[8:9], v[2:3] op_sel_hi:[0,1]
	s_waitcnt vmcnt(11)
	v_lshlrev_b32_e32 v60, 16, v10
	v_and_b32_e32 v61, 0xffff0000, v10
	v_mul_f32_e32 v10, v51, v51
	v_pk_fma_f32 v[2:3], v[50:51], v[50:51], v[2:3]
	s_waitcnt vmcnt(10)
; __device__ __forceinline__ float bf_lo(unsigned w) { return __uint_as_float(w << 16); }
; __device__ __forceinline__ float bf_hi(unsigned w) { return __uint_as_float(w & 0xffff0000u); }
; __device__ __forceinline__ float half_sum(float m) { auto rr = __builtin_amdgcn_permlane32_swap(__float_as_uint(m), __float_as_uint(m), false, false); return __uint_as_float(rr[0]) + __uint_as_float(rr[1]); }
; __device__ __forceinline__ void q_norm_rope(bf16x8 (&qf)[4], const float* gain, int pos, int hi_) {
;     ...
;     for (int ks = 0; ks < 4; ++ks) { const u32x4 w = __builtin_bit_cast(u32x4, qf[ks]);
; #pragma unroll
;         for (int i = 0; i < 4; ++i) { x[ks][2 * i] = bf_lo(w[i]); x[ks][2 * i + 1] = bf_hi(w[i]); } }
; #pragma unroll
;     for (int ks = 0; ks < 4; ++ks)
; #pragma unroll
;         for (int j = 0; j < 8; ++j) ss += x[ks][j] * x[ks][j];
;     ss = half_sum(ss);
;     const float rstd = 1.0f / sqrtf(ss * (1.f / 64.f) + EPS);
;     const float fpos = (float)pos;
; #pragma unroll
;     for (int ks = 0; ks < 2; ++ks) {
;         const f32x4 ga = *(const f32x4*)(gain + 16 * ks + 8 * hi), gb = *(const f32x4*)(gain + 16 * ks + 8 * hi + 4);
;         const f32x4 gc = *(const f32x4*)(gain + 32 + 16 * ks + 8 * hi), gd = *(const f32x4*)(gain + 32 + 16 * ks + 8 * hi + 4);
; #pragma unroll
;         for (int j = 0; j < 8; ++j) {
;             const int d = 16 * ks + 8 * hi + j;
;             const float invf = exp2f(-(float)d * (13.287712379549449f / 32.f));
;             const float ang = fpos * invf;
;             const float kq = rintf(ang * 0.15915494309189535f);
;             float rd = fmaf(-kq, 6.28318548202514648f, ang); rd = fmaf(-kq, -1.74845553e-07f, rd);
;             const float rv = rd * 0.15915494309189535f;
	v_lshlrev_b32_e32 v78, 16, v14
	v_and_b32_e32 v79, 0xffff0000, v14
	v_pk_add_f32 v[2:3], v[10:11], v[2:3] op_sel_hi:[0,1]
	v_lshlrev_b32_e32 v52, 16, v12
	v_and_b32_e32 v53, 0xffff0000, v12
	v_mul_f32_e32 v12, v79, v79
	v_pk_fma_f32 v[2:3], v[78:79], v[78:79], v[2:3]
	v_lshlrev_b32_e32 v74, 16, v15
	v_and_b32_e32 v75, 0xffff0000, v15
	v_pk_add_f32 v[2:3], v[12:13], v[2:3] op_sel_hi:[0,1]
	v_mul_f32_e32 v14, v75, v75
	v_pk_fma_f32 v[2:3], v[74:75], v[74:75], v[2:3]
	v_lshlrev_b32_e32 v70, 16, v16
	v_and_b32_e32 v71, 0xffff0000, v16
	v_pk_add_f32 v[2:3], v[14:15], v[2:3] op_sel_hi:[0,1]
	v_mul_f32_e32 v16, v71, v71
	v_pk_fma_f32 v[2:3], v[70:71], v[70:71], v[2:3]
	v_lshlrev_b32_e32 v66, 16, v17
	v_and_b32_e32 v67, 0xffff0000, v17
	v_pk_add_f32 v[2:3], v[16:17], v[2:3] op_sel_hi:[0,1]
	s_waitcnt vmcnt(9)
	v_lshlrev_b32_e32 v76, 16, v18
	v_and_b32_e32 v77, 0xffff0000, v18
	v_mul_f32_e32 v18, v67, v67
	v_pk_fma_f32 v[2:3], v[66:67], v[66:67], v[2:3]
	v_lshlrev_b32_e32 v68, 16, v20
	v_pk_add_f32 v[2:3], v[18:19], v[2:3] op_sel_hi:[0,1]
	v_and_b32_e32 v69, 0xffff0000, v20
	v_mul_f32_e32 v20, v61, v61
	v_pk_fma_f32 v[2:3], v[60:61], v[60:61], v[2:3]
	v_lshlrev_b32_e32 v56, 16, v11
	v_and_b32_e32 v57, 0xffff0000, v11
	v_pk_add_f32 v[2:3], v[20:21], v[2:3] op_sel_hi:[0,1]
	v_mul_f32_e32 v22, v57, v57
	v_pk_fma_f32 v[2:3], v[56:57], v[56:57], v[2:3]
	v_mul_f32_e32 v80, v53, v53
	v_pk_add_f32 v[2:3], v[22:23], v[2:3] op_sel_hi:[0,1]
	v_pk_fma_f32 v[2:3], v[52:53], v[52:53], v[2:3]
	v_lshlrev_b32_e32 v48, 16, v13
	v_and_b32_e32 v49, 0xffff0000, v13
	v_pk_add_f32 v[2:3], v[80:81], v[2:3] op_sel_hi:[0,1]
	v_mul_f32_e32 v82, v49, v49
	v_pk_fma_f32 v[2:3], v[48:49], v[48:49], v[2:3]
	v_mul_f32_e32 v84, v77, v77
	v_pk_add_f32 v[2:3], v[82:83], v[2:3] op_sel_hi:[0,1]
	v_pk_fma_f32 v[2:3], v[76:77], v[76:77], v[2:3]
	v_lshlrev_b32_e32 v72, 16, v19
	v_and_b32_e32 v73, 0xffff0000, v19
	v_pk_add_f32 v[2:3], v[84:85], v[2:3] op_sel_hi:[0,1]
	v_mul_f32_e32 v86, v73, v73
	v_pk_fma_f32 v[2:3], v[72:73], v[72:73], v[2:3]
	v_mul_f32_e32 v88, v69, v69
	v_pk_add_f32 v[2:3], v[86:87], v[2:3] op_sel_hi:[0,1]
	v_pk_fma_f32 v[2:3], v[68:69], v[68:69], v[2:3]
	v_lshlrev_b32_e32 v64, 16, v21
	v_and_b32_e32 v65, 0xffff0000, v21
	v_pk_add_f32 v[2:3], v[88:89], v[2:3] op_sel_hi:[0,1]
	v_mul_f32_e32 v90, v65, v65
	v_pk_fma_f32 v[2:3], v[64:65], v[64:65], v[2:3]
	v_mov_b32_e32 v23, 0
	v_pk_add_f32 v[2:3], v[90:91], v[2:3] op_sel_hi:[0,1]
	v_mov_b32_e32 v5, v2
	s_nop 1
	v_permlane32_swap_b32_e32 v2, v5
	v_mov_b32_e32 v22, 0
	v_mov_b32_e32 v21, 0
	v_mov_b32_e32 v20, 0
	v_mov_b32_e32 v19, 0
	v_mov_b32_e32 v18, 0
	v_mov_b32_e32 v17, 0
	v_mov_b32_e32 v16, 0
	v_mov_b32_e32 v3, v127
	s_cbranch_vccnz .LBB0_456
	v_ashrrev_i32_e32 v84, 2, v4
	v_and_b32_e32 v80, -8, v84
	v_add_u32_e32 v3, 16, v80
	v_cvt_f32_i32_e32 v3, v3
	s_waitcnt vmcnt(8)
	v_cvt_f32_i32_e32 v85, v0
	v_add_f32_e32 v0, v2, v5
	v_fmamk_f32 v0, v0, 0x3c800000, v137
	v_mul_f32_e32 v2, 0xbed49a78, v3
	v_cmp_gt_f32_e32 vcc, s18, v2
	v_add_u32_e32 v12, 18, v80
	v_cvt_f32_i32_e32 v12, v12
	v_cndmask_b32_e32 v2, 0, v139, vcc
	v_fmac_f32_e32 v2, 0xbed49a78, v3
	v_exp_f32_e32 v2, v2
	v_cndmask_b32_e32 v4, 0, v140, vcc
	v_mul_f32_e32 v3, 0x4f800000, v0
	v_cmp_gt_f32_e32 vcc, s19, v0
	v_ldexp_f32 v2, v2, v4
	v_mul_f32_e32 v2, v2, v85
	v_cndmask_b32_e32 v0, v0, v3, vcc
	v_mul_f32_e32 v4, 0.15915494, v2
	v_sqrt_f32_e32 v3, v0
	v_rndne_f32_e32 v4, v4
	v_fmac_f32_e32 v2, 0xc0c90fdb, v4
	v_fmac_f32_e32 v2, 0x343bbd2e, v4
	v_mul_f32_e32 v6, 0.15915494, v2
	v_add_u32_e32 v2, -1, v3
	v_fma_f32 v4, -v2, v3, v0
	v_cmp_ge_f32_e64 s[0:1], 0, v4
	v_add_u32_e32 v4, 1, v3
	v_sin_f32_e32 v42, v6
	v_cndmask_b32_e64 v2, v3, v2, s[0:1]
	v_fma_f32 v3, -v4, v3, v0
	v_cmp_lt_f32_e64 s[0:1], 0, v3
	v_cos_f32_e32 v82, v6
	v_readlane_b32 s36, v252, 37
	v_cndmask_b32_e64 v2, v2, v4, s[0:1]
	v_mul_f32_e32 v3, 0x37800000, v2
	v_cndmask_b32_e32 v2, v2, v3, vcc
	v_cmp_class_f32_e32 vcc, v0, v138
	v_ashrrev_i32_e32 v81, 31, v80
	v_readlane_b32 s48, v252, 49
	v_cndmask_b32_e32 v0, v2, v0, vcc
	v_div_scale_f32 v7, s[0:1], v0, v0, 1.0
	v_rcp_f32_e32 v8, v7
	v_readlane_b32 s49, v252, 50
	v_or_b32_e32 v87, 2, v80
	v_cvt_f32_i32_e32 v87, v87
	v_fma_f32 v9, -v7, v8, 1.0
	v_fmac_f32_e32 v8, v9, v8
	v_div_scale_f32 v9, vcc, 1.0, v0, 1.0
	v_mul_f32_e32 v10, v9, v8
	v_fma_f32 v11, -v7, v10, v9
	v_fmac_f32_e32 v10, v11, v8
	v_fma_f32 v7, -v7, v10, v9
	v_add_u32_e32 v9, 17, v80
	v_cvt_f32_i32_e32 v9, v9
	v_div_fmas_f32 v7, v7, v8, v10
	v_lshl_add_u64 v[26:27], v[80:81], 2, s[48:49]
	global_load_dwordx4 v[2:5], v[26:27], off offset:80
	global_load_dwordx4 v[18:21], v[26:27], off offset:64
	v_mul_f32_e32 v6, 0xbed49a78, v9
	v_cmp_gt_f32_e32 vcc, s18, v6
	v_div_fixup_f32 v0, v7, v0, 1.0
	v_or_b32_e32 v84, 7, v84
	v_cndmask_b32_e32 v6, 0, v139, vcc
	v_fmac_f32_e32 v6, 0xbed49a78, v9
	v_exp_f32_e32 v10, v6
	v_cndmask_b32_e32 v11, 0, v140, vcc
	global_load_dwordx4 v[6:9], v[26:27], off offset:208
	global_load_dwordx4 v[30:33], v[26:27], off offset:192
	v_cvt_f32_i32_e32 v84, v84
	v_ldexp_f32 v10, v10, v11
	v_mul_f32_e32 v10, v10, v85
	v_mul_f32_e32 v11, 0.15915494, v10
	v_rndne_f32_e32 v11, v11
	v_fmac_f32_e32 v10, 0xc0c90fdb, v11
	v_fmac_f32_e32 v10, 0x343bbd2e, v11
	v_mul_f32_e32 v11, 0xbed49a78, v12
	v_cmp_gt_f32_e32 vcc, s18, v11
	v_mul_f32_e32 v10, 0.15915494, v10
	v_sin_f32_e32 v43, v10
	v_cndmask_b32_e32 v11, 0, v139, vcc
	v_fmac_f32_e32 v11, 0xbed49a78, v12
	v_exp_f32_e32 v11, v11
	v_cos_f32_e32 v83, v10
	v_cndmask_b32_e32 v10, 0, v140, vcc
	v_add_u32_e32 v12, 19, v80
	v_ldexp_f32 v10, v11, v10
	v_mul_f32_e32 v10, v10, v85
	v_cvt_f32_i32_e32 v12, v12
	v_mul_f32_e32 v11, 0.15915494, v10
; __device__ __forceinline__ void q_norm_rope(bf16x8 (&qf)[4], const float* gain, int pos, int hi_) {
;     ...
; #pragma unroll
;         for (int j = 0; j < 8; ++j) {
;             const int d = 16 * ks + 8 * hi + j;
;             const float invf = exp2f(-(float)d * (13.287712379549449f / 32.f));
;             const float ang = fpos * invf;
;             const float kq = rintf(ang * 0.15915494309189535f);
;             float rd = fmaf(-kq, 6.28318548202514648f, ang); rd = fmaf(-kq, -1.74845553e-07f, rd);
;             const float rv = rd * 0.15915494309189535f;
;             const float cs = __builtin_amdgcn_cosf(rv), sn = __builtin_amdgcn_sinf(rv);
;             const float g1 = (j < 4) ? ga[j & 3] : gb[j & 3], g2 = (j < 4) ? gc[j & 3] : gd[j & 3];
;             const float y1 = x[ks][j] * rstd * g1, y2 = x[ks + 2][j] * rstd * g2;
	v_rndne_f32_e32 v11, v11
	v_fmac_f32_e32 v10, 0xc0c90fdb, v11
	v_fmac_f32_e32 v10, 0x343bbd2e, v11
	v_mul_f32_e32 v11, 0xbed49a78, v12
	v_cmp_gt_f32_e32 vcc, s18, v11
	v_mul_f32_e32 v10, 0.15915494, v10
	v_sin_f32_e32 v36, v10
	v_cndmask_b32_e32 v11, 0, v139, vcc
	v_fmac_f32_e32 v11, 0xbed49a78, v12
	v_exp_f32_e32 v11, v11
	v_cos_f32_e32 v34, v10
	v_cndmask_b32_e32 v10, 0, v140, vcc
	v_add_u32_e32 v12, 20, v80
	v_ldexp_f32 v10, v11, v10
	v_mul_f32_e32 v10, v10, v85
	v_cvt_f32_i32_e32 v12, v12
	v_mul_f32_e32 v11, 0.15915494, v10
	v_rndne_f32_e32 v11, v11
	v_fmac_f32_e32 v10, 0xc0c90fdb, v11
	v_fmac_f32_e32 v10, 0x343bbd2e, v11
	v_mul_f32_e32 v11, 0xbed49a78, v12
	v_cmp_gt_f32_e32 vcc, s18, v11
	v_mul_f32_e32 v10, 0.15915494, v10
	v_sin_f32_e32 v37, v10
	v_cndmask_b32_e32 v11, 0, v139, vcc
	v_fmac_f32_e32 v11, 0xbed49a78, v12
	v_exp_f32_e32 v11, v11
	v_cos_f32_e32 v35, v10
	v_cndmask_b32_e32 v10, 0, v140, vcc
	v_add_u32_e32 v12, 21, v80
	v_ldexp_f32 v10, v11, v10
	v_mul_f32_e32 v10, v10, v85
	v_cvt_f32_i32_e32 v12, v12
	v_mul_f32_e32 v11, 0.15915494, v10
	v_rndne_f32_e32 v11, v11
	v_fmac_f32_e32 v10, 0xc0c90fdb, v11
	v_fmac_f32_e32 v10, 0x343bbd2e, v11
	v_mul_f32_e32 v11, 0xbed49a78, v12
	v_cmp_gt_f32_e32 vcc, s18, v11
	v_mul_f32_e32 v10, 0.15915494, v10
	v_sin_f32_e32 v40, v10
	v_cndmask_b32_e32 v11, 0, v139, vcc
	v_fmac_f32_e32 v11, 0xbed49a78, v12
	v_exp_f32_e32 v11, v11
	v_cos_f32_e32 v38, v10
	v_cndmask_b32_e32 v10, 0, v140, vcc
	v_add_u32_e32 v12, 22, v80
	v_ldexp_f32 v10, v11, v10
	v_mul_f32_e32 v10, v10, v85
	v_cvt_f32_i32_e32 v12, v12
	v_mul_f32_e32 v11, 0.15915494, v10
	v_rndne_f32_e32 v11, v11
	v_fmac_f32_e32 v10, 0xc0c90fdb, v11
	v_fmac_f32_e32 v10, 0x343bbd2e, v11
	v_mul_f32_e32 v11, 0xbed49a78, v12
	v_cmp_gt_f32_e32 vcc, s18, v11
	v_mul_f32_e32 v10, 0.15915494, v10
	v_sin_f32_e32 v41, v10
	v_cndmask_b32_e32 v11, 0, v139, vcc
	v_fmac_f32_e32 v11, 0xbed49a78, v12
	v_exp_f32_e32 v11, v11
	v_cos_f32_e32 v39, v10
	v_cndmask_b32_e32 v10, 0, v140, vcc
	v_add_u32_e32 v12, 23, v80
	v_ldexp_f32 v10, v11, v10
	v_mul_f32_e32 v10, v10, v85
	v_cvt_f32_i32_e32 v12, v12
	v_mul_f32_e32 v11, 0.15915494, v10
	v_rndne_f32_e32 v11, v11
	v_fmac_f32_e32 v10, 0xc0c90fdb, v11
	v_fmac_f32_e32 v10, 0x343bbd2e, v11
	v_mul_f32_e32 v11, 0xbed49a78, v12
	v_cmp_gt_f32_e32 vcc, s18, v11
	v_mul_f32_e32 v10, 0.15915494, v10
	v_sin_f32_e32 v46, v10
	v_cndmask_b32_e32 v11, 0, v139, vcc
	v_fmac_f32_e32 v11, 0xbed49a78, v12
	v_exp_f32_e32 v11, v11
	v_cos_f32_e32 v44, v10
	v_cndmask_b32_e32 v10, 0, v140, vcc
	v_cvt_f32_i32_e32 v12, v80
	v_ldexp_f32 v10, v11, v10
	v_mul_f32_e32 v10, v10, v85
	v_mul_f32_e32 v11, 0.15915494, v10
	v_rndne_f32_e32 v11, v11
	v_fmac_f32_e32 v10, 0xc0c90fdb, v11
	v_fmac_f32_e32 v10, 0x343bbd2e, v11
	v_mul_f32_e32 v11, 0xbed49a78, v12
	v_cmp_gt_f32_e32 vcc, s18, v11
	v_mul_f32_e32 v10, 0.15915494, v10
	v_sin_f32_e32 v47, v10
	v_cndmask_b32_e32 v11, 0, v139, vcc
	v_fmac_f32_e32 v11, 0xbed49a78, v12
	v_exp_f32_e32 v11, v11
	v_cos_f32_e32 v45, v10
	v_cndmask_b32_e32 v10, 0, v140, vcc
	v_pk_mul_f32 v[76:77], v[0:1], v[76:77] op_sel_hi:[0,1]
	v_ldexp_f32 v10, v11, v10
	v_mul_f32_e32 v10, v10, v85
	v_mul_f32_e32 v11, 0.15915494, v10
	v_rndne_f32_e32 v11, v11
	v_fmac_f32_e32 v10, 0xc0c90fdb, v11
	v_fmac_f32_e32 v10, 0x343bbd2e, v11
	v_mul_f32_e32 v14, 0.15915494, v10
	v_or_b32_e32 v10, 1, v80
	v_cvt_f32_i32_e32 v15, v10
	v_sin_f32_e32 v90, v14
	v_cos_f32_e32 v92, v14
	global_load_dwordx4 v[10:13], v[26:27], off offset:16
	global_load_dwordx4 v[22:25], v[26:27], off
	v_mul_f32_e32 v14, 0xbed49a78, v15
	v_cmp_gt_f32_e32 vcc, s18, v14
	v_pk_mul_f32 v[78:79], v[0:1], v[78:79] op_sel_hi:[0,1]
	s_waitcnt vmcnt(2)
	v_pk_mul_f32 v[30:31], v[76:77], v[30:31]
	v_cndmask_b32_e32 v14, 0, v139, vcc
	v_fmac_f32_e32 v14, 0xbed49a78, v15
	v_exp_f32_e32 v81, v14
	v_cndmask_b32_e32 v86, 0, v140, vcc
	global_load_dwordx4 v[14:17], v[26:27], off offset:144
	s_nop 0
	global_load_dwordx4 v[26:29], v[26:27], off offset:128
	v_pk_mul_f32 v[18:19], v[78:79], v[18:19]
	v_ldexp_f32 v81, v81, v86
	v_mul_f32_e32 v81, v81, v85
	v_mul_f32_e32 v86, 0.15915494, v81
	v_rndne_f32_e32 v86, v86
	v_fmac_f32_e32 v81, 0xc0c90fdb, v86
	v_fmac_f32_e32 v81, 0x343bbd2e, v86
	v_mul_f32_e32 v86, 0xbed49a78, v87
	v_cmp_gt_f32_e32 vcc, s18, v86
	v_mul_f32_e32 v81, 0.15915494, v81
	v_sin_f32_e32 v91, v81
	v_cndmask_b32_e32 v86, 0, v139, vcc
	v_fmac_f32_e32 v86, 0xbed49a78, v87
	v_exp_f32_e32 v86, v86
	v_cos_f32_e32 v93, v81
	v_cndmask_b32_e32 v81, 0, v140, vcc
	v_or_b32_e32 v87, 3, v80
	v_ldexp_f32 v81, v86, v81
	v_mul_f32_e32 v81, v81, v85
	v_cvt_f32_i32_e32 v87, v87
	v_mul_f32_e32 v86, 0.15915494, v81
	v_rndne_f32_e32 v86, v86
	v_fmac_f32_e32 v81, 0xc0c90fdb, v86
	v_fmac_f32_e32 v81, 0x343bbd2e, v86
	v_mul_f32_e32 v86, 0xbed49a78, v87
	v_cmp_gt_f32_e32 vcc, s18, v86
	v_mul_f32_e32 v81, 0.15915494, v81
	v_sin_f32_e32 v116, v81
	v_cndmask_b32_e32 v86, 0, v139, vcc
	v_fmac_f32_e32 v86, 0xbed49a78, v87
	v_exp_f32_e32 v86, v86
	v_cos_f32_e32 v94, v81
	v_cndmask_b32_e32 v81, 0, v140, vcc
	v_or_b32_e32 v87, 4, v80
	v_ldexp_f32 v81, v86, v81
	v_mul_f32_e32 v81, v81, v85
	v_cvt_f32_i32_e32 v87, v87
	v_mul_f32_e32 v86, 0.15915494, v81
	v_rndne_f32_e32 v86, v86
	v_fmac_f32_e32 v81, 0xc0c90fdb, v86
	v_fmac_f32_e32 v81, 0x343bbd2e, v86
	v_mul_f32_e32 v86, 0xbed49a78, v87
	v_cmp_gt_f32_e32 vcc, s18, v86
	v_mul_f32_e32 v81, 0.15915494, v81
	v_sin_f32_e32 v117, v81
	v_cndmask_b32_e32 v86, 0, v139, vcc
	v_fmac_f32_e32 v86, 0xbed49a78, v87
	v_exp_f32_e32 v86, v86
	v_cos_f32_e32 v95, v81
	v_cndmask_b32_e32 v81, 0, v140, vcc
	v_or_b32_e32 v87, 5, v80
	v_ldexp_f32 v81, v86, v81
	v_mul_f32_e32 v81, v81, v85
; __device__ __forceinline__ void q_norm_rope(bf16x8 (&qf)[4], const float* gain, int pos, int hi_) {
;     ...
;         const f32x4 ga = *(const f32x4*)(gain + 16 * ks + 8 * hi), gb = *(const f32x4*)(gain + 16 * ks + 8 * hi + 4);
;         const f32x4 gc = *(const f32x4*)(gain + 32 + 16 * ks + 8 * hi), gd = *(const f32x4*)(gain + 32 + 16 * ks + 8 * hi + 4);
; #pragma unroll
;         for (int j = 0; j < 8; ++j) {
;             const int d = 16 * ks + 8 * hi + j;
;             const float invf = exp2f(-(float)d * (13.287712379549449f / 32.f));
;             const float ang = fpos * invf;
;             const float kq = rintf(ang * 0.15915494309189535f);
;             float rd = fmaf(-kq, 6.28318548202514648f, ang); rd = fmaf(-kq, -1.74845553e-07f, rd);
;             const float rv = rd * 0.15915494309189535f;
;             const float cs = __builtin_amdgcn_cosf(rv), sn = __builtin_amdgcn_sinf(rv);
;             const float g1 = (j < 4) ? ga[j & 3] : gb[j & 3], g2 = (j < 4) ? gc[j & 3] : gd[j & 3];
;             const float y1 = x[ks][j] * rstd * g1, y2 = x[ks + 2][j] * rstd * g2;
;             x[ks][j] = (y1 * cs - y2 * sn) * QS; x[ks + 2][j] = (y2 * cs + y1 * sn) * QS;
; __device__ __forceinline__ void swa_unit(int b, int kvh, int qb, const bf16* U, const bf16* VTb, bf16* Y, const float* sinks, const float* qgain, const int* pos, unsigned char* lds, int wid, int lane) {
;     ...
;         float m = sinks[qh] * LOG2E, l = (hi == 0) ? 1.f : 0.f;
	v_cvt_f32_i32_e32 v87, v87
	v_mul_f32_e32 v86, 0.15915494, v81
	v_rndne_f32_e32 v86, v86
	v_fmac_f32_e32 v81, 0xc0c90fdb, v86
	v_fmac_f32_e32 v81, 0x343bbd2e, v86
	v_mul_f32_e32 v86, 0xbed49a78, v87
	v_cmp_gt_f32_e32 vcc, s18, v86
	v_mul_f32_e32 v81, 0.15915494, v81
	v_sin_f32_e32 v120, v81
	v_cndmask_b32_e32 v86, 0, v139, vcc
	v_fmac_f32_e32 v86, 0xbed49a78, v87
	v_exp_f32_e32 v86, v86
	v_cos_f32_e32 v118, v81
	v_cndmask_b32_e32 v81, 0, v140, vcc
	v_or_b32_e32 v80, 6, v80
	v_ldexp_f32 v81, v86, v81
	v_mul_f32_e32 v81, v81, v85
	v_cvt_f32_i32_e32 v80, v80
	v_mul_f32_e32 v86, 0.15915494, v81
	v_rndne_f32_e32 v86, v86
	v_fmac_f32_e32 v81, 0xc0c90fdb, v86
	v_fmac_f32_e32 v81, 0x343bbd2e, v86
	v_mul_f32_e32 v86, 0xbed49a78, v80
	v_cmp_gt_f32_e32 vcc, s18, v86
	v_mul_f32_e32 v81, 0.15915494, v81
	v_sin_f32_e32 v121, v81
	v_cndmask_b32_e32 v86, 0, v139, vcc
	v_fmac_f32_e32 v86, 0xbed49a78, v80
	v_exp_f32_e32 v80, v86
	v_cos_f32_e32 v119, v81
	v_cndmask_b32_e32 v81, 0, v140, vcc
	v_pk_mul_f32 v[76:77], v[82:83], v[30:31]
	v_ldexp_f32 v80, v80, v81
	v_mul_f32_e32 v80, v80, v85
	v_mul_f32_e32 v81, 0.15915494, v80
	v_rndne_f32_e32 v81, v81
	v_fmac_f32_e32 v80, 0xc0c90fdb, v81
	v_fmac_f32_e32 v80, 0x343bbd2e, v81
	v_mul_f32_e32 v81, 0xbed49a78, v84
	v_pk_mul_f32 v[30:31], v[42:43], v[30:31]
	v_readlane_b32 s37, v252, 38
	v_readlane_b32 s38, v252, 39
	v_readlane_b32 s39, v252, 40
	v_readlane_b32 s40, v252, 41
	v_readlane_b32 s41, v252, 42
	v_readlane_b32 s42, v252, 43
	v_readlane_b32 s43, v252, 44
	v_readlane_b32 s44, v252, 45
	v_readlane_b32 s45, v252, 46
	v_readlane_b32 s46, v252, 47
	v_readlane_b32 s47, v252, 48
	v_readlane_b32 s50, v252, 51
	v_readlane_b32 s51, v252, 52
	v_cmp_gt_f32_e32 vcc, s18, v81
	v_pk_fma_f32 v[76:77], v[42:43], v[18:19], v[76:77]
	v_pk_fma_f32 v[18:19], v[82:83], v[18:19], v[30:31] neg_lo:[0,0,1] neg_hi:[0,0,1]
	s_mov_b32 s15, s3
	v_cndmask_b32_e32 v81, 0, v139, vcc
	v_pk_mul_f32 v[18:19], v[18:19], s[10:11] op_sel_hi:[1,0]
	s_lshl_b64 s[0:1], s[14:15], 2
	v_readlane_b32 s36, v252, 2
	v_fmac_f32_e32 v81, 0xbed49a78, v84
	v_cvt_pk_bf16_f32 v84, v18, v19
	v_pk_mul_f32 v[18:19], v[0:1], v[74:75] op_sel_hi:[0,1]
	v_readlane_b32 s37, v252, 3
	s_add_u32 s0, s36, s0
	v_pk_mul_f32 v[18:19], v[18:19], v[20:21]
	v_pk_mul_f32 v[20:21], v[0:1], v[72:73] op_sel_hi:[0,1]
	s_addc_u32 s1, s37, s1
	v_pk_mul_f32 v[20:21], v[20:21], v[32:33]
	global_load_dword v32, v1, s[0:1]
	v_exp_f32_e32 v81, v81
	v_mul_f32_e32 v80, 0.15915494, v80
	v_pk_mul_f32 v[30:31], v[34:35], v[20:21]
	v_pk_mul_f32 v[20:21], v[36:37], v[20:21]
	v_sin_f32_e32 v124, v80
	v_cos_f32_e32 v122, v80
	v_cndmask_b32_e32 v80, 0, v140, vcc
	v_pk_fma_f32 v[30:31], v[36:37], v[18:19], v[30:31]
	v_pk_fma_f32 v[18:19], v[34:35], v[18:19], v[20:21] neg_lo:[0,0,1] neg_hi:[0,0,1]
	v_ldexp_f32 v80, v81, v80
	v_pk_mul_f32 v[18:19], v[18:19], s[10:11] op_sel_hi:[1,0]
	v_mul_f32_e32 v80, v80, v85
	v_cvt_pk_bf16_f32 v85, v18, v19
	v_pk_mul_f32 v[18:19], v[0:1], v[70:71] op_sel_hi:[0,1]
	v_pk_mul_f32 v[2:3], v[18:19], v[2:3]
	v_pk_mul_f32 v[18:19], v[0:1], v[68:69] op_sel_hi:[0,1]
	v_pk_mul_f32 v[6:7], v[18:19], v[6:7]
	v_mul_f32_e32 v81, 0.15915494, v80
	v_pk_mul_f32 v[18:19], v[38:39], v[6:7]
	v_pk_mul_f32 v[6:7], v[40:41], v[6:7]
	v_pk_fma_f32 v[18:19], v[40:41], v[2:3], v[18:19]
	v_pk_fma_f32 v[2:3], v[38:39], v[2:3], v[6:7] neg_lo:[0,0,1] neg_hi:[0,0,1]
	v_rndne_f32_e32 v81, v81
	v_pk_mul_f32 v[2:3], v[2:3], s[10:11] op_sel_hi:[1,0]
	v_fmac_f32_e32 v80, 0xc0c90fdb, v81
	v_cvt_pk_bf16_f32 v86, v2, v3
	v_pk_mul_f32 v[2:3], v[0:1], v[66:67] op_sel_hi:[0,1]
	v_pk_mul_f32 v[2:3], v[2:3], v[4:5]
	v_pk_mul_f32 v[4:5], v[0:1], v[64:65] op_sel_hi:[0,1]
	v_pk_mul_f32 v[4:5], v[4:5], v[8:9]
	v_fmac_f32_e32 v80, 0x343bbd2e, v81
	v_pk_mul_f32 v[6:7], v[44:45], v[4:5]
	v_pk_mul_f32 v[4:5], v[46:47], v[4:5]
	v_pk_fma_f32 v[6:7], v[46:47], v[2:3], v[6:7]
	v_pk_fma_f32 v[2:3], v[44:45], v[2:3], v[4:5] neg_lo:[0,0,1] neg_hi:[0,0,1]
	v_pk_mul_f32 v[4:5], v[0:1], v[60:61] op_sel_hi:[0,1]
	v_pk_mul_f32 v[2:3], v[2:3], s[10:11] op_sel_hi:[1,0]
	v_pk_mul_f32 v[6:7], v[6:7], s[10:11] op_sel_hi:[1,0]
	v_cvt_pk_bf16_f32 v87, v2, v3
	v_pk_mul_f32 v[2:3], v[0:1], v[62:63] op_sel_hi:[0,1]
	s_waitcnt vmcnt(1)
; __device__ __forceinline__ unsigned cvtpk(float lo, float hi) { f32x2_t v = {lo, hi}; bf16x2_t b = __builtin_convertvector(v, bf16x2_t); return __builtin_bit_cast(unsigned, b); }
; __device__ __forceinline__ void q_norm_rope(bf16x8 (&qf)[4], const float* gain, int pos, int hi_) {
;     ...
;             x[ks][j] = (y1 * cs - y2 * sn) * QS; x[ks + 2][j] = (y2 * cs + y1 * sn) * QS;
;         }
;     }
; #pragma unroll
;     for (int ks = 0; ks < 4; ++ks) { u32x4 w;
; #pragma unroll
;         for (int i = 0; i < 4; ++i) w[i] = cvtpk(x[ks][2 * i], x[ks][2 * i + 1]);
;         qf[ks] = __builtin_bit_cast(bf16x8, w); }
; __device__ __forceinline__ void swa_unit(int b, int kvh, int qb, const bf16* U, const bf16* VTb, bf16* Y, const float* sinks, const float* qgain, const int* pos, unsigned char* lds, int wid, int lane) {
;     ...
;         float m = sinks[qh] * LOG2E, l = (hi == 0) ? 1.f : 0.f;
;         f32x16 o[2]; o[0] = f32x16{}; o[1] = f32x16{};
	v_pk_mul_f32 v[4:5], v[4:5], v[26:27]
	v_cvt_pk_bf16_f32 v83, v6, v7
	v_pk_mul_f32 v[2:3], v[2:3], v[22:23]
	v_pk_mul_f32 v[6:7], v[92:93], v[4:5]
	v_pk_mul_f32 v[4:5], v[90:91], v[4:5]
	v_pk_fma_f32 v[6:7], v[90:91], v[2:3], v[6:7]
	v_pk_fma_f32 v[2:3], v[92:93], v[2:3], v[4:5] neg_lo:[0,0,1] neg_hi:[0,0,1]
	v_pk_mul_f32 v[4:5], v[0:1], v[56:57] op_sel_hi:[0,1]
	v_pk_mul_f32 v[2:3], v[2:3], s[10:11] op_sel_hi:[1,0]
	v_pk_mul_f32 v[6:7], v[6:7], s[10:11] op_sel_hi:[1,0]
	v_cvt_pk_bf16_f32 v92, v2, v3
	v_pk_mul_f32 v[2:3], v[0:1], v[58:59] op_sel_hi:[0,1]
	v_pk_mul_f32 v[4:5], v[4:5], v[28:29]
	v_cvt_pk_bf16_f32 v88, v6, v7
	v_pk_mul_f32 v[2:3], v[2:3], v[24:25]
	v_pk_mul_f32 v[6:7], v[94:95], v[4:5]
	v_pk_mul_f32 v[4:5], v[116:117], v[4:5]
	v_pk_fma_f32 v[6:7], v[116:117], v[2:3], v[6:7]
	v_pk_fma_f32 v[2:3], v[94:95], v[2:3], v[4:5] neg_lo:[0,0,1] neg_hi:[0,0,1]
	v_pk_mul_f32 v[4:5], v[0:1], v[52:53] op_sel_hi:[0,1]
	v_pk_mul_f32 v[2:3], v[2:3], s[10:11] op_sel_hi:[1,0]
	v_mul_f32_e32 v80, 0.15915494, v80
	v_pk_mul_f32 v[6:7], v[6:7], s[10:11] op_sel_hi:[1,0]
	v_cvt_pk_bf16_f32 v93, v2, v3
	v_pk_mul_f32 v[2:3], v[0:1], v[54:55] op_sel_hi:[0,1]
	v_pk_mul_f32 v[4:5], v[4:5], v[14:15]
	v_sin_f32_e32 v125, v80
	v_cos_f32_e32 v123, v80
	v_cvt_pk_bf16_f32 v89, v6, v7
	v_pk_mul_f32 v[2:3], v[2:3], v[10:11]
	v_pk_mul_f32 v[6:7], v[118:119], v[4:5]
	v_pk_mul_f32 v[4:5], v[120:121], v[4:5]
	v_pk_fma_f32 v[6:7], v[120:121], v[2:3], v[6:7]
	v_pk_fma_f32 v[2:3], v[118:119], v[2:3], v[4:5] neg_lo:[0,0,1] neg_hi:[0,0,1]
	v_pk_mul_f32 v[4:5], v[0:1], v[48:49] op_sel_hi:[0,1]
	v_pk_mul_f32 v[2:3], v[2:3], s[10:11] op_sel_hi:[1,0]
	v_pk_mul_f32 v[6:7], v[6:7], s[10:11] op_sel_hi:[1,0]
	v_cvt_pk_bf16_f32 v94, v2, v3
	v_pk_mul_f32 v[2:3], v[0:1], v[50:51] op_sel_hi:[0,1]
	v_pk_mul_f32 v[4:5], v[4:5], v[16:17]
	v_cvt_pk_bf16_f32 v90, v6, v7
	v_pk_mul_f32 v[2:3], v[2:3], v[12:13]
	v_pk_mul_f32 v[6:7], v[122:123], v[4:5]
	v_pk_mul_f32 v[4:5], v[124:125], v[4:5]
	v_pk_fma_f32 v[6:7], v[124:125], v[2:3], v[6:7]
	v_pk_fma_f32 v[2:3], v[122:123], v[2:3], v[4:5] neg_lo:[0,0,1] neg_hi:[0,0,1]
	v_pk_mul_f32 v[30:31], v[30:31], s[10:11] op_sel_hi:[1,0]
	v_pk_mul_f32 v[18:19], v[18:19], s[10:11] op_sel_hi:[1,0]
	v_pk_mul_f32 v[6:7], v[6:7], s[10:11] op_sel_hi:[1,0]
	v_pk_mul_f32 v[2:3], v[2:3], s[10:11] op_sel_hi:[1,0]
	v_mov_b32_e32 v14, v1
	v_mov_b32_e32 v15, v1
	v_pk_mul_f32 v[76:77], v[76:77], s[10:11] op_sel_hi:[1,0]
	v_cvt_pk_bf16_f32 v81, v30, v31
	v_cvt_pk_bf16_f32 v82, v18, v19
	v_cvt_pk_bf16_f32 v91, v6, v7
	v_cvt_pk_bf16_f32 v95, v2, v3
	s_waitcnt vmcnt(0)
	v_mul_f32_e32 v124, 0x3fb8aa3b, v32
	v_mov_b32_e32 v0, v1
	v_mov_b32_e32 v2, v1
	v_mov_b32_e32 v3, v1
	v_mov_b32_e32 v4, v1
	v_mov_b32_e32 v5, v1
	v_mov_b32_e32 v6, v1
	v_mov_b32_e32 v7, v1
	v_mov_b32_e32 v8, v1
	v_mov_b32_e32 v9, v1
	v_mov_b32_e32 v10, v1
	v_mov_b32_e32 v11, v1
	v_mov_b32_e32 v12, v1
	v_mov_b32_e32 v13, v1
	v_mov_b64_e32 v[30:31], v[14:15]
	v_mov_b64_e32 v[46:47], v[14:15]
	v_cvt_pk_bf16_f32 v80, v76, v77
	s_mov_b32 s0, s28
	s_mov_b32 s1, s27
	v_mov_b32_e32 v116, v142
	v_mov_b64_e32 v[28:29], v[12:13]
	v_mov_b64_e32 v[26:27], v[10:11]
	v_mov_b64_e32 v[24:25], v[8:9]
	v_mov_b64_e32 v[22:23], v[6:7]
	v_mov_b64_e32 v[20:21], v[4:5]
	v_mov_b64_e32 v[18:19], v[2:3]
	v_mov_b64_e32 v[16:17], v[0:1]
	v_mov_b64_e32 v[44:45], v[12:13]
	v_mov_b64_e32 v[42:43], v[10:11]
	v_mov_b64_e32 v[40:41], v[8:9]
	v_mov_b64_e32 v[38:39], v[6:7]
	v_mov_b64_e32 v[36:37], v[4:5]
	v_mov_b64_e32 v[34:35], v[2:3]
	v_mov_b64_e32 v[32:33], v[0:1]
	v_mov_b32_e32 v3, v127
	v_readlane_b32 s38, v252, 4
	v_readlane_b32 s39, v252, 5
	v_readlane_b32 s40, v252, 6
	v_readlane_b32 s41, v252, 7
	v_readlane_b32 s42, v252, 8
	v_readlane_b32 s43, v252, 9
	v_readlane_b32 s44, v252, 10
	v_readlane_b32 s45, v252, 11
	v_readlane_b32 s46, v252, 12
	v_readlane_b32 s47, v252, 13
	v_readlane_b32 s48, v252, 14
	v_readlane_b32 s49, v252, 15
	v_readlane_b32 s50, v252, 16
	v_readlane_b32 s51, v252, 17

; #define LAS __attribute__((address_space(3)))
; #define MFMA32(a, b, c) __builtin_amdgcn_mfma_f32_32x32x16_bf16((a), (b), (c), 0, 0, 0)
; __device__ __forceinline__ void sb_unit(int b, int h, int qb, const bf16* U, const bf16* VT, bf16* Y, unsigned char* lds, int wid, int lane, int& res_lo, int& res_hi) {
;     ...
;             const LAS unsigned char* Kb = kfp + (t & 7) * 16384; const LAS unsigned char* Vb = vfp + (t & 7) * 16384;
;             f32x16 y0 = f32x16{}, y1 = f32x16{};
; #pragma unroll
;             for (int ks = 0; ks < 4; ++ks) { const bf16x8 a0 = *(const LAS bf16x8*)(Kb + kofs[ks]), a1 = *(const LAS bf16x8*)(Kb + 4096 + kofs[ks]); y0 = MFMA32(a0, qf[ks], y0); y1 = MFMA32(a1, qf[ks], y1); }
; #pragma unroll
;             for (int r = 0; r < 16; ++r) { y0[r] = fminf(y0[r], 100.f); y1[r] = fminf(y1[r], 100.f); }
;             if (t == mytile) {
;                 int tqm = tq - 64 * t - 8 * hi; asm volatile("" : "+v"(tqm));
; #pragma unroll
;                 for (int r = 0; r < 16; ++r) { const int key = 16 * (r >> 3) + (r & 7); if (key >= tqm) y0[r] = -INFINITY; if (key + 32 >= tqm) y1[r] = -INFINITY; }
;             }
.LBB0_726:
	s_and_b32 s69, s82, 0x1c000
	v_add_u32_e32 v0, s69, v154
	v_add_u32_e32 v6, v0, v146
	v_add_u32_e32 v10, v0, v148
	ds_read_b128 v[212:215], v6
	ds_read_b128 v[216:219], v6 offset:4096
	ds_read_b128 v[220:223], v10
	ds_read_b128 v[224:227], v10 offset:4096
	v_add_u32_e32 v10, v0, v150
	v_add_u32_e32 v0, v0, v152
	ds_read_b128 v[228:231], v10
	ds_read_b128 v[232:235], v10 offset:4096
	ds_read_b128 v[236:239], v0
	ds_read_b128 v[240:243], v0 offset:4096
	s_cmp_lg_u32 s96, s89
	s_waitcnt lgkmcnt(7)
	v_mfma_f32_32x32x16_bf16 v[64:79], v[212:215], v[100:103], 0
	s_waitcnt lgkmcnt(6)
	v_mfma_f32_32x32x16_bf16 v[80:95], v[216:219], v[100:103], 0
	s_waitcnt lgkmcnt(5)
	v_mfma_f32_32x32x16_bf16 v[64:79], v[220:223], v[104:107], v[64:79]
	s_waitcnt lgkmcnt(4)
	v_mfma_f32_32x32x16_bf16 v[80:95], v[224:227], v[104:107], v[80:95]
	s_waitcnt lgkmcnt(3)
	v_mfma_f32_32x32x16_bf16 v[64:79], v[228:231], v[108:111], v[64:79]
	s_waitcnt lgkmcnt(2)
	v_mfma_f32_32x32x16_bf16 v[80:95], v[232:235], v[108:111], v[80:95]
	s_waitcnt lgkmcnt(1)
	v_mfma_f32_32x32x16_bf16 v[64:79], v[236:239], v[112:115], v[64:79]
	s_waitcnt lgkmcnt(0)
	v_mfma_f32_32x32x16_bf16 v[80:95], v[240:243], v[112:115], v[80:95]
	s_nop 9
	v_min_f32_e32 v0, 0x42c80000, v64
	v_min_f32_e32 v3, 0x42c80000, v65
	v_min_f32_e32 v4, 0x42c80000, v66
	v_min_f32_e32 v7, 0x42c80000, v67
	v_min_f32_e32 v9, 0x42c80000, v68
	v_min_f32_e32 v12, 0x42c80000, v69
	v_min_f32_e32 v13, 0x42c80000, v70
	v_min_f32_e32 v15, 0x42c80000, v71
	v_min_f32_e32 v157, 0x42c80000, v73
	v_min_f32_e32 v159, 0x42c80000, v74
	v_min_f32_e32 v161, 0x42c80000, v75
	v_min_f32_e32 v164, 0x42c80000, v76
	v_min_f32_e32 v165, 0x42c80000, v77
	v_min_f32_e32 v167, 0x42c80000, v78
	v_min_f32_e32 v169, 0x42c80000, v79
	v_min_f32_e32 v2, 0x42c80000, v80
	v_min_f32_e32 v5, 0x42c80000, v81
	v_min_f32_e32 v81, 0x42c80000, v72
	v_min_f32_e32 v6, 0x42c80000, v82
	v_min_f32_e32 v8, 0x42c80000, v83
	v_min_f32_e32 v10, 0x42c80000, v84
	v_min_f32_e32 v11, 0x42c80000, v85
	v_min_f32_e32 v14, 0x42c80000, v86
	v_min_f32_e32 v80, 0x42c80000, v87
	v_min_f32_e32 v82, 0x42c80000, v88
	v_min_f32_e32 v158, 0x42c80000, v89
	v_min_f32_e32 v160, 0x42c80000, v90
	v_min_f32_e32 v162, 0x42c80000, v91
	v_min_f32_e32 v163, 0x42c80000, v92
	v_min_f32_e32 v166, 0x42c80000, v93
	v_min_f32_e32 v168, 0x42c80000, v94
	v_min_f32_e32 v170, 0x42c80000, v95
	s_cbranch_scc1 .LBB0_728
	v_mov_b32_e32 v64, v156
	s_nop 0
	v_cmp_lt_i32_e64 s[60:61], 22, v64
	v_cmp_lt_i32_e64 s[64:65], 23, v64
	v_cmp_lt_i32_e64 s[58:59], 21, v64
	s_or_b64 s[60:61], s[64:65], s[60:61]
	v_cmp_lt_i32_e64 s[56:57], 20, v64
	s_or_b64 s[58:59], s[60:61], s[58:59]
	v_cmp_lt_i32_e64 s[54:55], 19, v64
	s_or_b64 s[56:57], s[58:59], s[56:57]
	v_cmp_lt_i32_e64 s[52:53], 18, v64
	s_or_b64 s[54:55], s[56:57], s[54:55]
	v_cmp_lt_i32_e64 s[50:51], 17, v64
	s_or_b64 s[52:53], s[54:55], s[52:53]
	v_cmp_lt_i32_e64 s[48:49], 16, v64
	s_or_b64 s[50:51], s[52:53], s[50:51]
	v_cmp_lt_i32_e64 s[46:47], 7, v64
	s_or_b64 s[48:49], s[50:51], s[48:49]
	v_cmp_lt_i32_e64 s[44:45], 6, v64
	s_or_b64 s[46:47], s[48:49], s[46:47]
	v_cmp_lt_i32_e64 s[42:43], 5, v64
	s_or_b64 s[44:45], s[46:47], s[44:45]
	v_cmp_lt_i32_e64 s[40:41], 4, v64
	s_or_b64 s[42:43], s[44:45], s[42:43]
	v_cmp_lt_i32_e64 s[38:39], 3, v64
	s_or_b64 s[40:41], s[42:43], s[40:41]
	v_cmp_lt_i32_e64 s[36:37], 2, v64
	s_or_b64 s[38:39], s[40:41], s[38:39]
	v_cmp_lt_i32_e64 s[34:35], 1, v64
	s_or_b64 s[36:37], s[38:39], s[36:37]
	v_cmp_lt_i32_e64 s[30:31], 0, v64
	s_or_b64 s[34:35], s[36:37], s[34:35]
	s_or_b64 s[30:31], s[34:35], s[30:31]
	v_cmp_lt_i32_e64 s[62:63], 54, v64
	v_cndmask_b32_e64 v0, v145, v0, s[30:31]
	v_cmp_lt_i32_e64 s[30:31], 55, v64
	v_cmp_lt_i32_e64 s[28:29], 53, v64
	v_cmp_lt_i32_e64 s[26:27], 52, v64
	v_cndmask_b32_e64 v170, v145, v170, s[30:31]
	s_or_b64 s[30:31], s[30:31], s[62:63]
	s_or_b64 s[28:29], s[30:31], s[28:29]
	v_cmp_lt_i32_e64 s[24:25], 51, v64
	s_or_b64 s[26:27], s[28:29], s[26:27]
	v_cmp_lt_i32_e64 s[22:23], 50, v64
	s_or_b64 s[24:25], s[26:27], s[24:25]
	v_cmp_lt_i32_e64 s[20:21], 49, v64
	s_or_b64 s[22:23], s[24:25], s[22:23]
	v_cmp_lt_i32_e64 s[18:19], 48, v64
	s_or_b64 s[20:21], s[22:23], s[20:21]
	v_cmp_lt_i32_e64 s[16:17], 39, v64
	s_or_b64 s[18:19], s[20:21], s[18:19]
	v_cmp_lt_i32_e64 s[14:15], 38, v64
	s_or_b64 s[16:17], s[18:19], s[16:17]
	v_cmp_lt_i32_e64 s[12:13], 37, v64
	s_or_b64 s[14:15], s[16:17], s[14:15]
	v_cmp_lt_i32_e64 s[10:11], 36, v64
	s_or_b64 s[12:13], s[14:15], s[12:13]
	v_cmp_lt_i32_e64 s[8:9], 35, v64
	s_or_b64 s[10:11], s[12:13], s[10:11]
	v_cmp_lt_i32_e64 s[6:7], 34, v64
	s_or_b64 s[8:9], s[10:11], s[8:9]
	v_cmp_lt_i32_e64 s[2:3], 33, v64
	s_or_b64 s[6:7], s[8:9], s[6:7]
	v_cmp_lt_i32_e32 vcc, 32, v64
	s_or_b64 s[2:3], s[6:7], s[2:3]
	s_or_b64 vcc, s[2:3], vcc
	v_cndmask_b32_e64 v169, v145, v169, s[64:65]
	v_cndmask_b32_e64 v167, v145, v167, s[60:61]
	v_cndmask_b32_e64 v165, v145, v165, s[58:59]
	v_cndmask_b32_e64 v164, v145, v164, s[56:57]
	v_cndmask_b32_e64 v161, v145, v161, s[54:55]
	v_cndmask_b32_e64 v159, v145, v159, s[52:53]
	v_cndmask_b32_e64 v157, v145, v157, s[50:51]
	v_cndmask_b32_e64 v81, v145, v81, s[48:49]
	v_cndmask_b32_e64 v15, v145, v15, s[46:47]
	v_cndmask_b32_e64 v13, v145, v13, s[44:45]
	v_cndmask_b32_e64 v12, v145, v12, s[42:43]
	v_cndmask_b32_e64 v9, v145, v9, s[40:41]
	v_cndmask_b32_e64 v7, v145, v7, s[38:39]
	v_cndmask_b32_e64 v4, v145, v4, s[36:37]
	v_cndmask_b32_e64 v3, v145, v3, s[34:35]
	v_cndmask_b32_e64 v168, v145, v168, s[30:31]
	v_cndmask_b32_e64 v166, v145, v166, s[28:29]
	v_cndmask_b32_e64 v163, v145, v163, s[26:27]
	v_cndmask_b32_e64 v162, v145, v162, s[24:25]
	v_cndmask_b32_e64 v160, v145, v160, s[22:23]
	v_cndmask_b32_e64 v158, v145, v158, s[20:21]
	v_cndmask_b32_e64 v82, v145, v82, s[18:19]
	v_cndmask_b32_e64 v80, v145, v80, s[16:17]
	v_cndmask_b32_e64 v14, v145, v14, s[14:15]
	v_cndmask_b32_e64 v11, v145, v11, s[12:13]
	v_cndmask_b32_e64 v10, v145, v10, s[10:11]
	v_cndmask_b32_e64 v8, v145, v8, s[8:9]
	v_cndmask_b32_e64 v6, v145, v6, s[6:7]
	v_cndmask_b32_e64 v5, v145, v5, s[2:3]
	v_cndmask_b32_e32 v2, v145, v2, vcc
; #define LAS __attribute__((address_space(3)))
; #define MFMA32(a, b, c) __builtin_amdgcn_mfma_f32_32x32x16_bf16((a), (b), (c), 0, 0, 0)
; __device__ __forceinline__ void sb_unit(int b, int h, int qb, const bf16* U, const bf16* VT, bf16* Y, unsigned char* lds, int wid, int lane, int& res_lo, int& res_hi) {
;     ...
;             f32x16 l0, l1;
; #pragma unroll
;             for (int r = 0; r < 16; ++r) { l0[r] = __builtin_amdgcn_logf(1.f + __builtin_amdgcn_exp2f(y0[r])); l1[r] = __builtin_amdgcn_logf(1.f + __builtin_amdgcn_exp2f(y1[r])); }
;             bf16x8 lb[4]; lb[0] = pack8(l0, 0); lb[1] = pack8(l0, 8); lb[2] = pack8(l1, 0); lb[3] = pack8(l1, 8);
; #pragma unroll
;             for (int r = 0; r < 16; ++r) { y0[r] -= l0[r]; y1[r] -= l1[r]; }
;             f32x16 X = MFMA32(JN, lb[2], C); X = MFMA32(JN, lb[3], X);
;             f32x16 f1 = MFMA32(TM[0], lb[2], C); f1 = MFMA32(TM[1], lb[3], f1);
;             f32x16 f0 = MFMA32(TM[0], lb[0], X); f0 = MFMA32(TM[1], lb[1], f0);
;             C = MFMA32(JN, lb[0], X); C = MFMA32(JN, lb[1], C);
; #pragma unroll
;             for (int r = 0; r < 16; ++r) { y0[r] = __builtin_amdgcn_exp2f(y0[r] + f0[r]); y1[r] = __builtin_amdgcn_exp2f(y1[r] + f1[r]); }
;             bf16x8 pk[4]; pk[0] = pack8(y0, 0); pk[1] = pack8(y0, 8); pk[2] = pack8(y1, 0); pk[3] = pack8(y1, 8);
; #pragma unroll
;             for (int db = 0; db < 2; ++db)
; #pragma unroll
;                 for (int kk = 0; kk < 4; ++kk) { const bf16x8 vf = *(const LAS bf16x8*)(Vb + db * 4096 + vofs[kk]); o[db] = MFMA32(vf, pk[kk], o[db]); }
.LBB0_728:
	v_exp_f32_e32 v64, v0
	v_exp_f32_e32 v65, v2
	v_exp_f32_e32 v66, v3
	s_mov_b32 s70, s68
	v_add_f32_e32 v64, 1.0, v64
	v_log_f32_e32 v83, v64
	v_add_f32_e32 v64, 1.0, v65
	v_log_f32_e32 v92, v64
	v_exp_f32_e32 v64, v5
	v_add_f32_e32 v65, 1.0, v66
	v_log_f32_e32 v93, v65
	v_exp_f32_e32 v65, v4
	v_add_f32_e32 v64, 1.0, v64
	v_log_f32_e32 v94, v64
	v_exp_f32_e32 v64, v6
	v_add_f32_e32 v65, 1.0, v65
	v_log_f32_e32 v95, v65
	v_exp_f32_e32 v65, v7
	v_add_f32_e32 v64, 1.0, v64
	v_log_f32_e32 v184, v64
	v_exp_f32_e32 v64, v8
	v_add_f32_e32 v65, 1.0, v65
	v_log_f32_e32 v185, v65
	v_exp_f32_e32 v65, v9
	v_add_f32_e32 v64, 1.0, v64
	v_log_f32_e32 v186, v64
	v_exp_f32_e32 v64, v10
	v_add_f32_e32 v65, 1.0, v65
	v_log_f32_e32 v187, v65
	v_exp_f32_e32 v65, v12
	v_add_f32_e32 v64, 1.0, v64
	v_log_f32_e32 v188, v64
	v_exp_f32_e32 v64, v11
	v_add_f32_e32 v65, 1.0, v65
	v_log_f32_e32 v189, v65
	v_exp_f32_e32 v65, v13
	v_add_f32_e32 v64, 1.0, v64
	v_log_f32_e32 v190, v64
	v_exp_f32_e32 v64, v14
	v_add_f32_e32 v65, 1.0, v65
	v_log_f32_e32 v191, v65
	v_exp_f32_e32 v65, v15
	v_add_f32_e32 v64, 1.0, v64
	v_log_f32_e32 v192, v64
	v_exp_f32_e32 v64, v80
	v_add_f32_e32 v65, 1.0, v65
	v_log_f32_e32 v193, v65
	v_exp_f32_e32 v65, v81
	v_add_f32_e32 v64, 1.0, v64
	v_log_f32_e32 v194, v64
	v_exp_f32_e32 v64, v82
	v_add_f32_e32 v65, 1.0, v65
	v_log_f32_e32 v195, v65
	v_exp_f32_e32 v65, v157
	v_add_f32_e32 v64, 1.0, v64
	v_log_f32_e32 v196, v64
	v_exp_f32_e32 v64, v158
	v_add_f32_e32 v65, 1.0, v65
	v_log_f32_e32 v197, v65
	v_exp_f32_e32 v65, v159
	v_add_f32_e32 v64, 1.0, v64
	v_log_f32_e32 v198, v64
	v_exp_f32_e32 v64, v160
	v_add_f32_e32 v65, 1.0, v65
	v_log_f32_e32 v199, v65
	v_exp_f32_e32 v65, v161
	v_add_f32_e32 v64, 1.0, v64
	v_log_f32_e32 v200, v64
	v_exp_f32_e32 v64, v162
	v_add_f32_e32 v65, 1.0, v65
	v_log_f32_e32 v201, v65
	v_exp_f32_e32 v65, v164
	v_add_f32_e32 v64, 1.0, v64
	v_log_f32_e32 v202, v64
	v_exp_f32_e32 v64, v163
	v_add_f32_e32 v65, 1.0, v65
	v_log_f32_e32 v203, v65
	v_exp_f32_e32 v65, v165
	v_add_f32_e32 v64, 1.0, v64
	v_log_f32_e32 v204, v64
	v_exp_f32_e32 v64, v166
	v_add_f32_e32 v65, 1.0, v65
	v_log_f32_e32 v205, v65
	v_exp_f32_e32 v65, v167
	v_add_f32_e32 v64, 1.0, v64
	v_log_f32_e32 v206, v64
	v_exp_f32_e32 v64, v168
	v_add_f32_e32 v65, 1.0, v65
	s_mov_b32 s71, s68
	v_add_u32_e32 v171, s69, v155
	v_log_f32_e32 v207, v65
	v_exp_f32_e32 v65, v169
	s_mov_b32 s69, s68
	v_mov_b64_e32 v[178:179], s[70:71]
	v_exp_f32_e32 v66, v170
	v_mov_b64_e32 v[176:177], s[68:69]
	v_add_f32_e32 v64, 1.0, v64
	v_log_f32_e32 v208, v64
	v_add_f32_e32 v64, 1.0, v65
	v_log_f32_e32 v209, v64
	v_add_f32_e32 v64, 1.0, v66
	v_cvt_pk_bf16_f32 v84, v92, v94
	v_cvt_pk_bf16_f32 v85, v184, v186
	v_cvt_pk_bf16_f32 v86, v188, v190
	v_cvt_pk_bf16_f32 v87, v192, v194
	v_log_f32_e32 v210, v64
	v_cvt_pk_bf16_f32 v88, v196, v198
	v_mfma_f32_32x32x16_bf16 v[64:79], v[176:179], v[84:87], v[48:63]
	v_cvt_pk_bf16_f32 v89, v200, v202
	v_cvt_pk_bf16_f32 v90, v204, v206
	v_cvt_pk_bf16_f32 v91, v208, v210
	v_cvt_pk_bf16_f32 v172, v83, v93
	v_cvt_pk_bf16_f32 v173, v95, v185
	v_cvt_pk_bf16_f32 v174, v187, v189
	v_cvt_pk_bf16_f32 v175, v191, v193
	v_mfma_f32_32x32x16_bf16 v[64:79], v[176:179], v[88:91], v[64:79]
	v_sub_f32_e32 v0, v0, v83
	v_sub_f32_e32 v2, v2, v92
	v_sub_f32_e32 v3, v3, v93
	v_sub_f32_e32 v5, v5, v94
	v_sub_f32_e32 v4, v4, v95
	v_sub_f32_e32 v6, v6, v184
	v_sub_f32_e32 v7, v7, v185
	v_mfma_f32_32x32x16_bf16 v[48:63], v[96:99], v[84:87], v[48:63]
	v_sub_f32_e32 v8, v8, v186
	v_sub_f32_e32 v184, v80, v194
	v_sub_f32_e32 v185, v81, v195
	v_sub_f32_e32 v186, v82, v196
	v_cvt_pk_bf16_f32 v180, v195, v197
	v_cvt_pk_bf16_f32 v181, v199, v201
	v_cvt_pk_bf16_f32 v182, v203, v205
	v_mfma_f32_32x32x16_bf16 v[48:63], v[116:119], v[88:91], v[48:63]
	v_cvt_pk_bf16_f32 v183, v207, v209
	v_sub_f32_e32 v9, v9, v187
	v_sub_f32_e32 v10, v10, v188
	v_sub_f32_e32 v12, v12, v189
	v_sub_f32_e32 v11, v11, v190
	v_sub_f32_e32 v13, v13, v191
	v_sub_f32_e32 v14, v14, v192
	v_mfma_f32_32x32x16_bf16 v[80:95], v[96:99], v[172:175], v[64:79]
	s_nop 3
	v_add_f32_e32 v2, v2, v48
	v_sub_f32_e32 v15, v15, v193
	v_sub_f32_e32 v157, v157, v197
	v_sub_f32_e32 v158, v158, v198
	v_sub_f32_e32 v159, v159, v199
	v_sub_f32_e32 v160, v160, v200
	v_sub_f32_e32 v161, v161, v201
	v_mfma_f32_32x32x16_bf16 v[80:95], v[116:119], v[180:183], v[80:95]
	v_sub_f32_e32 v162, v162, v202
	v_sub_f32_e32 v164, v164, v203
	v_sub_f32_e32 v163, v163, v204
	v_sub_f32_e32 v165, v165, v205
	v_sub_f32_e32 v166, v166, v206
	v_sub_f32_e32 v167, v167, v207
	v_sub_f32_e32 v168, v168, v208
	s_nop 4
	v_add_f32_e32 v0, v0, v80
	v_exp_f32_e32 v80, v2
	v_add_f32_e32 v2, v3, v81
	v_exp_f32_e32 v48, v2
	v_add_f32_e32 v2, v5, v49
	v_exp_f32_e32 v81, v2
	v_add_f32_e32 v2, v4, v82
	v_exp_f32_e32 v49, v2
	v_add_f32_e32 v2, v6, v50
	v_exp_f32_e32 v82, v2
	v_add_f32_e32 v2, v7, v83
	v_exp_f32_e32 v7, v2
	v_add_f32_e32 v2, v8, v51
	v_exp_f32_e32 v83, v2
	v_add_f32_e32 v2, v9, v84
	v_exp_f32_e32 v8, v2
	v_add_f32_e32 v2, v10, v52
	v_exp_f32_e32 v84, v2
	v_add_f32_e32 v2, v12, v85
	v_exp_f32_e32 v9, v2
	v_add_f32_e32 v2, v11, v53
	v_exp_f32_e32 v85, v2
	v_add_f32_e32 v2, v13, v86
	v_exp_f32_e32 v10, v2
	v_add_f32_e32 v2, v14, v54
	v_exp_f32_e32 v14, v2
	v_add_f32_e32 v2, v15, v87
	v_exp_f32_e32 v11, v2
	v_add_f32_e32 v2, v184, v55
	v_exp_f32_e32 v15, v2
	v_add_f32_e32 v2, v185, v88
	v_exp_f32_e32 v52, v2
	v_add_f32_e32 v2, v186, v56
	v_exp_f32_e32 v88, v2
	v_add_f32_e32 v2, v157, v89
	v_exp_f32_e32 v53, v2
	v_add_f32_e32 v2, v158, v57
	v_exp_f32_e32 v89, v2
	v_add_f32_e32 v2, v159, v90
	v_exp_f32_e32 v54, v2
	v_add_f32_e32 v2, v160, v58
	v_exp_f32_e32 v90, v2
	v_add_f32_e32 v2, v161, v91
	v_exp_f32_e32 v55, v2
	v_add_f32_e32 v2, v162, v59
	v_exp_f32_e32 v91, v2
	v_add_f32_e32 v2, v164, v92
	v_exp_f32_e32 v56, v2
	v_add_f32_e32 v2, v163, v60
	v_exp_f32_e32 v60, v2
	v_add_f32_e32 v2, v165, v93
	v_exp_f32_e32 v57, v2
	v_add_f32_e32 v2, v166, v61
	v_exp_f32_e32 v61, v2
	v_add_f32_e32 v2, v167, v94
	v_exp_f32_e32 v58, v2
	v_add_f32_e32 v2, v168, v62
	v_add_u32_e32 v50, v171, v147
	v_exp_f32_e32 v0, v0
	v_exp_f32_e32 v62, v2
	ds_read_b128 v[2:5], v50 offset:8192
	v_sub_f32_e32 v169, v169, v209
	v_add_f32_e32 v6, v169, v95
	v_exp_f32_e32 v59, v6
	v_cvt_pk_bf16_f32 v6, v0, v48
	v_add_u32_e32 v0, v171, v149
	v_cvt_pk_bf16_f32 v7, v49, v7
	v_cvt_pk_bf16_f32 v8, v8, v9
	v_cvt_pk_bf16_f32 v9, v10, v11
	ds_read_b128 v[10:13], v0 offset:8192
	ds_read_b128 v[48:51], v50 offset:12288
	s_waitcnt lgkmcnt(2)
; #define LAS __attribute__((address_space(3)))
; #define MFMA32(a, b, c) __builtin_amdgcn_mfma_f32_32x32x16_bf16((a), (b), (c), 0, 0, 0)
; __device__ __forceinline__ void sb_unit(int b, int h, int qb, const bf16* U, const bf16* VT, bf16* Y, unsigned char* lds, int wid, int lane, int& res_lo, int& res_hi) {
;     ...
;             f32x16 X = MFMA32(JN, lb[2], C); X = MFMA32(JN, lb[3], X);
;             f32x16 f1 = MFMA32(TM[0], lb[2], C); f1 = MFMA32(TM[1], lb[3], f1);
;             f32x16 f0 = MFMA32(TM[0], lb[0], X); f0 = MFMA32(TM[1], lb[1], f0);
;             C = MFMA32(JN, lb[0], X); C = MFMA32(JN, lb[1], C);
; #pragma unroll
;             for (int r = 0; r < 16; ++r) { y0[r] = __builtin_amdgcn_exp2f(y0[r] + f0[r]); y1[r] = __builtin_amdgcn_exp2f(y1[r] + f1[r]); }
;             bf16x8 pk[4]; pk[0] = pack8(y0, 0); pk[1] = pack8(y0, 8); pk[2] = pack8(y1, 0); pk[3] = pack8(y1, 8);
; #pragma unroll
;             for (int db = 0; db < 2; ++db)
; #pragma unroll
;                 for (int kk = 0; kk < 4; ++kk) { const bf16x8 vf = *(const LAS bf16x8*)(Vb + db * 4096 + vofs[kk]); o[db] = MFMA32(vf, pk[kk], o[db]); }
;             alive = __any(C[0] > -160.f);
;         }
	v_mfma_f32_32x32x16_bf16 v[32:47], v[2:5], v[6:9], v[32:47]
	v_add_u32_e32 v86, v171, v151
	v_cvt_pk_bf16_f32 v2, v52, v53
	v_cvt_pk_bf16_f32 v3, v54, v55
	v_cvt_pk_bf16_f32 v4, v56, v57
	v_cvt_pk_bf16_f32 v5, v58, v59
	ds_read_b128 v[52:55], v86 offset:8192
	ds_read_b128 v[56:59], v0 offset:12288
	v_sub_f32_e32 v170, v170, v210
	s_waitcnt lgkmcnt(2)
	v_mfma_f32_32x32x16_bf16 v[16:31], v[48:51], v[6:9], v[16:31]
	v_add_u32_e32 v0, v171, v153
	s_mov_b32 s2, 0xc3200000
	v_mfma_f32_32x32x16_bf16 v[32:47], v[10:13], v[2:5], v[32:47]
	v_cvt_pk_bf16_f32 v13, v14, v15
	v_add_f32_e32 v14, v170, v63
	v_cvt_pk_bf16_f32 v10, v80, v81
	v_cvt_pk_bf16_f32 v11, v82, v83
	v_cvt_pk_bf16_f32 v12, v84, v85
	ds_read_b128 v[80:83], v0 offset:8192
	ds_read_b128 v[84:87], v86 offset:12288
	v_exp_f32_e32 v14, v14
	s_waitcnt lgkmcnt(2)
	v_mfma_f32_32x32x16_bf16 v[16:31], v[56:59], v[2:5], v[16:31]
	v_mfma_f32_32x32x16_bf16 v[32:47], v[52:55], v[10:13], v[32:47]
	v_cvt_pk_bf16_f32 v54, v60, v61
	v_cvt_pk_bf16_f32 v55, v62, v14
	ds_read_b128 v[60:63], v0 offset:12288
	v_cvt_pk_bf16_f32 v52, v88, v89
	v_cvt_pk_bf16_f32 v53, v90, v91
	v_mfma_f32_32x32x16_bf16 v[64:79], v[176:179], v[172:175], v[64:79]
	s_waitcnt lgkmcnt(1)
	v_mfma_f32_32x32x16_bf16 v[16:31], v[84:87], v[10:13], v[16:31]
	v_mfma_f32_32x32x16_bf16 v[32:47], v[80:83], v[52:55], v[32:47]
	s_waitcnt lgkmcnt(0)
	v_mfma_f32_32x32x16_bf16 v[16:31], v[60:63], v[52:55], v[16:31]
	v_mfma_f32_32x32x16_bf16 v[48:63], v[176:179], v[180:183], v[64:79]
	s_nop 11
	v_cmp_lt_f32_e32 vcc, s2, v48
	s_cmp_lg_u64 vcc, 0
	s_cselect_b64 s[2:3], -1, 0
	s_add_i32 s6, s89, -1
	s_cmp_gt_i32 s89, s87
	s_cselect_b64 s[8:9], -1, 0
	s_and_b64 s[8:9], s[8:9], s[2:3]
	s_andn2_b64 vcc, exec, s[8:9]
	s_addk_i32 s82, 0xc000
	s_cbranch_vccnz .LBB0_733
	s_mov_b32 s89, s6
	s_branch .LBB0_726
